# adds sample-row mini-GEMM loops rewritten to issue all 16 operand loads per 256-wide K chunk up front with counted vmcnt waits (was three serialized load-wait groups per chunk)
# speedup vs baseline: 1.0391x; 1.0067x over previous
; __device__ __forceinline__ int tidx() { int t = (int)__builtin_amdgcn_workitem_id_x(); asm volatile("" : "+v"(t)); return t; }
; __device__ __forceinline__ unsigned cvt_pk_bf16(float lo, float hi) { unsigned r; asm("v_cvt_pk_bf16_f32 %0, %1, %2" : "=v"(r) : "v"(lo), "v"(hi)); return r; }
; __device__ __forceinline__ float sigm(float x) { return rcpf_(1.f + __expf(-x)); }
; __device__ __forceinline__ float lo_bf(unsigned w) { return __uint_as_float(w << 16); }
; __device__ __forceinline__ f32x4 mini_tile(const bf16_t* __restrict__ A, const bf16_t* __restrict__ Bt, int K, int m0, int n0, int lane) {
;     const bf16_t* ap = A + (size_t)(m0 + (lane & 15)) * K + 8 * (lane >> 4);
;     const bf16_t* bp = Bt + (size_t)(n0 + (lane & 15)) * K + 8 * (lane >> 4);
;     f32x4 acc0 = (f32x4){0.f, 0.f, 0.f, 0.f}, acc1 = (f32x4){0.f, 0.f, 0.f, 0.f};
; #pragma unroll 1
;     for (int k0 = 0; k0 < K; k0 += 256) {
;         bf16x8 a[8], b[8];
; #pragma unroll
;         for (int i = 0; i < 8; ++i) { a[i] = *(const bf16x8*)(ap + k0 + 32 * i); b[i] = *(const bf16x8*)(bp + k0 + 32 * i); }
; #pragma unroll
;         for (int i = 0; i < 8; i += 2) { acc0 = __builtin_amdgcn_mfma_f32_16x16x32_bf16(b[i], a[i], acc0, 0, 0, 0); acc1 = __builtin_amdgcn_mfma_f32_16x16x32_bf16(b[i + 1], a[i + 1], acc1, 0, 0, 0); }
;     }
;     return acc0 + acc1;
; }
; __device__ __forceinline__ void mini_branch(const Params& p, int l, int bid, int nblk) {
;     const int tid = tidx(), wid = tid >> 6, lane = tid & 63, g = lane >> 4;
;     for (int s = bid; s < 256; s += nblk) {
;         const int m0 = SEQ + 16 * (s >> 3), n0 = 128 * (s & 7) + 16 * wid, m = m0 + (lane & 15), n = n0 + 4 * g;
;         f32x4 val = (f32x4){0.f, 0.f, 0.f, 0.f};
; #pragma unroll 1
;         for (int z = 0; z < 3; ++z) {
;             const f32x4 acc = mini_tile(p.Y + (size_t)z * MROWS * 1024, p.WbrT + (size_t)(l * 3 + z) * 1048576, 1024, m0, n0, lane);
;             const u32x2 gw = *(const u32x2*)(p.P + (size_t)m * NIN + C_GM + z * 1024 + n);
;             val[0] += sigm(lo_bf(gw.x)) * acc[0]; val[1] += sigm(hi_bf(gw.x)) * acc[1]; val[2] += sigm(lo_bf(gw.y)) * acc[2]; val[3] += sigm(hi_bf(gw.y)) * acc[3];
;         }
;         u32x2 w; w.x = cvt_pk_bf16(val[0], val[1]); w.y = cvt_pk_bf16(val[2], val[3]);
;         *(u32x2*)(p.merged + (size_t)m * 1024 + n) = w;
.LBB0_221:
	v_lshl_add_u64 v[68:69], v[26:27], 0, v[4:5]
	v_lshl_add_u64 v[66:67], v[24:25], 0, v[4:5]
	global_load_dwordx4 v[34:37], v[68:69], off
	global_load_dwordx4 v[42:45], v[66:67], off
	global_load_dwordx4 v[38:41], v[68:69], off offset:64
	global_load_dwordx4 v[46:49], v[66:67], off offset:64
	global_load_dwordx4 v[50:53], v[68:69], off offset:128
	global_load_dwordx4 v[54:57], v[66:67], off offset:128
	global_load_dwordx4 v[58:61], v[68:69], off offset:192
	global_load_dwordx4 v[62:65], v[66:67], off offset:192
	global_load_dwordx4 v[70:73], v[68:69], off offset:256
	global_load_dwordx4 v[74:77], v[66:67], off offset:256
	global_load_dwordx4 v[78:81], v[68:69], off offset:320
	global_load_dwordx4 v[82:85], v[66:67], off offset:320
	global_load_dwordx4 v[86:89], v[68:69], off offset:384
	global_load_dwordx4 v[90:93], v[66:67], off offset:384
	global_load_dwordx4 v[94:97], v[68:69], off offset:448
	global_load_dwordx4 v[98:101], v[66:67], off offset:448
	s_addk_i32 s16, 0x100
	v_lshl_add_u64 v[26:27], v[26:27], 0, s[54:55]
	s_cmpk_lt_u32 s16, 0x300
	v_lshl_add_u64 v[24:25], v[24:25], 0, s[54:55]
	s_waitcnt vmcnt(14)
	v_mfma_f32_16x16x32_bf16 v[0:3], v[34:37], v[42:45], v[0:3]
	s_waitcnt vmcnt(12)
	v_mfma_f32_16x16x32_bf16 v[6:9], v[38:41], v[46:49], v[6:9]
	s_waitcnt vmcnt(10)
	v_mfma_f32_16x16x32_bf16 v[0:3], v[50:53], v[54:57], v[0:3]
	s_waitcnt vmcnt(8)
	v_mfma_f32_16x16x32_bf16 v[6:9], v[58:61], v[62:65], v[6:9]
	s_waitcnt vmcnt(6)
	v_mfma_f32_16x16x32_bf16 v[0:3], v[70:73], v[74:77], v[0:3]
	s_waitcnt vmcnt(4)
	v_mfma_f32_16x16x32_bf16 v[6:9], v[78:81], v[82:85], v[6:9]
	s_waitcnt vmcnt(2)
	v_mfma_f32_16x16x32_bf16 v[0:3], v[86:89], v[90:93], v[0:3]
	s_waitcnt vmcnt(0)
	v_mfma_f32_16x16x32_bf16 v[6:9], v[94:97], v[98:101], v[6:9]
	s_cbranch_scc1 .LBB0_221
	s_lshl_b32 s50, s9, 11
	v_lshl_add_u64 v[24:25], v[18:19], 0, s[50:51]
	global_load_dwordx2 v[24:25], v[24:25], off
	s_nop 3
	v_pk_add_f32 v[2:3], v[2:3], v[8:9]
	v_pk_add_f32 v[0:1], v[0:1], v[6:7]
	s_add_i32 s9, s9, 1
	s_mov_b64 s[16:17], 0x200000
	v_lshl_add_u64 v[10:11], v[10:11], 0, s[16:17]
	s_cmp_eq_u32 s9, 3
	v_lshl_add_u64 v[14:15], v[14:15], 0, s[60:61]
	s_waitcnt vmcnt(0)
	v_lshlrev_b32_e32 v6, 16, v24
	v_and_b32_e32 v7, 0xffff0000, v24
	v_lshlrev_b32_e32 v8, 16, v25
	v_and_b32_e32 v9, 0xffff0000, v25
	v_mul_f32_e32 v6, 0xbfb8aa3b, v6
	v_mul_f32_e32 v7, 0xbfb8aa3b, v7
	v_mul_f32_e32 v8, 0xbfb8aa3b, v8
	v_mul_f32_e32 v9, 0xbfb8aa3b, v9
	v_exp_f32_e32 v6, v6
	v_exp_f32_e32 v7, v7
	v_exp_f32_e32 v8, v8
	v_exp_f32_e32 v9, v9
	v_add_f32_e32 v6, 1.0, v6
	v_add_f32_e32 v7, 1.0, v7
	v_add_f32_e32 v8, 1.0, v8
	v_add_f32_e32 v9, 1.0, v9
	v_rcp_f32_e32 v6, v6
	v_rcp_f32_e32 v7, v7
	v_rcp_f32_e32 v8, v8
	v_rcp_f32_e32 v9, v9
	v_pk_fma_f32 v[22:23], v[0:1], v[6:7], v[22:23]
	v_pk_fma_f32 v[20:21], v[2:3], v[8:9], v[20:21]
	s_cbranch_scc0 .LBB0_220
	v_lshlrev_b64 v[0:1], 11, v[16:17]
	v_lshl_add_u64 v[0:1], s[18:19], 0, v[0:1]
	s_add_i32 s8, s8, s42
	s_add_i32 s4, s4, s5
	s_add_i32 s6, s6, s7
	v_lshl_add_u64 v[0:1], v[12:13], 1, v[0:1]
	s_cmpk_gt_i32 s8, 0xff
	v_cvt_pk_bf16_f32 v2, v22, v23
	v_cvt_pk_bf16_f32 v3, v20, v21
	global_store_dwordx2 v[0:1], v[2:3], off
	s_cbranch_scc0 .LBB0_219

; __device__ __forceinline__ f32x4 mini_tile(const bf16_t* __restrict__ A, const bf16_t* __restrict__ Bt, int K, int m0, int n0, int lane) {
;     const bf16_t* ap = A + (size_t)(m0 + (lane & 15)) * K + 8 * (lane >> 4);
;     const bf16_t* bp = Bt + (size_t)(n0 + (lane & 15)) * K + 8 * (lane >> 4);
;     f32x4 acc0 = (f32x4){0.f, 0.f, 0.f, 0.f}, acc1 = (f32x4){0.f, 0.f, 0.f, 0.f};
; #pragma unroll 1
;     for (int k0 = 0; k0 < K; k0 += 256) {
;         bf16x8 a[8], b[8];
; #pragma unroll
;         for (int i = 0; i < 8; ++i) { a[i] = *(const bf16x8*)(ap + k0 + 32 * i); b[i] = *(const bf16x8*)(bp + k0 + 32 * i); }
; #pragma unroll
;         for (int i = 0; i < 8; i += 2) { acc0 = __builtin_amdgcn_mfma_f32_16x16x32_bf16(b[i], a[i], acc0, 0, 0, 0); acc1 = __builtin_amdgcn_mfma_f32_16x16x32_bf16(b[i + 1], a[i + 1], acc1, 0, 0, 0); }
;     }
;     return acc0 + acc1;
; }
; __device__ __forceinline__ void mini_branch(const Params& p, int l, int bid, int nblk) {
;     const int tid = tidx(), wid = tid >> 6, lane = tid & 63, g = lane >> 4;
;     for (int s = bid; s < 256; s += nblk) {
;         const int m0 = SEQ + 16 * (s >> 3), n0 = 128 * (s & 7) + 16 * wid, m = m0 + (lane & 15), n = n0 + 4 * g;
;         f32x4 val = (f32x4){0.f, 0.f, 0.f, 0.f};
; #pragma unroll 1
;         for (int z = 0; z < 3; ++z) {
;             const f32x4 acc = mini_tile(p.Y + (size_t)z * MROWS * 1024, p.WbrT + (size_t)(l * 3 + z) * 1048576, 1024, m0, n0, lane);
;             const u32x2 gw = *(const u32x2*)(p.P + (size_t)m * NIN + C_GM + z * 1024 + n);
;             val[0] += sigm(lo_bf(gw.x)) * acc[0]; val[1] += sigm(hi_bf(gw.x)) * acc[1]; val[2] += sigm(lo_bf(gw.y)) * acc[2]; val[3] += sigm(hi_bf(gw.y)) * acc[3];
;         }
;         u32x2 w; w.x = cvt_pk_bf16(val[0], val[1]); w.y = cvt_pk_bf16(val[2], val[3]);
;         *(u32x2*)(p.merged + (size_t)m * 1024 + n) = w;
;     }
; }
; __device__ __forceinline__ void mini_res(const float* Xin, float* Xo, bf16_t* Xbo, const bf16_t* A, const bf16_t* Bt, int K, float* sumsq, int bid, int nblk) {
;     const int tid = tidx(), wid = tid >> 6, lane = tid & 63, g = lane >> 4;
;     for (int s = bid; s < 256; s += nblk) {
;         const int m0 = SEQ + 16 * (s >> 3), n0 = 128 * (s & 7) + 16 * wid, m = m0 + (lane & 15), n = n0 + 4 * g;
;         const f32x4 acc = mini_tile(A, Bt, K, m0, n0, lane);
;         float* xp = Xo + (size_t)m * 1024 + n;
.LBB0_802:
	v_lshl_add_u64 v[48:49], v[10:11], 0, v[4:5]
	v_lshl_add_u64 v[46:47], v[12:13], 0, v[4:5]
	global_load_dwordx4 v[18:21], v[48:49], off
	global_load_dwordx4 v[22:25], v[46:47], off
	global_load_dwordx4 v[26:29], v[48:49], off offset:64
	global_load_dwordx4 v[30:33], v[46:47], off offset:64
	global_load_dwordx4 v[34:37], v[48:49], off offset:128
	global_load_dwordx4 v[38:41], v[46:47], off offset:128
	global_load_dwordx4 v[42:45], v[48:49], off offset:192
	global_load_dwordx4 v[50:53], v[46:47], off offset:192
	global_load_dwordx4 v[54:57], v[48:49], off offset:256
	global_load_dwordx4 v[58:61], v[46:47], off offset:256
	global_load_dwordx4 v[62:65], v[48:49], off offset:320
	global_load_dwordx4 v[66:69], v[46:47], off offset:320
	global_load_dwordx4 v[70:73], v[48:49], off offset:384
	global_load_dwordx4 v[74:77], v[46:47], off offset:384
	global_load_dwordx4 v[78:81], v[48:49], off offset:448
	global_load_dwordx4 v[82:85], v[46:47], off offset:448
	s_addk_i32 s4, 0x100
	v_lshl_add_u64 v[10:11], v[10:11], 0, s[54:55]
	s_cmp_lt_u32 s4, s49
	v_lshl_add_u64 v[12:13], v[12:13], 0, s[54:55]
	s_waitcnt vmcnt(14)
	v_mfma_f32_16x16x32_bf16 v[0:3], v[18:21], v[22:25], v[0:3]
	s_waitcnt vmcnt(12)
	v_mfma_f32_16x16x32_bf16 v[6:9], v[26:29], v[30:33], v[6:9]
	s_waitcnt vmcnt(10)
	v_mfma_f32_16x16x32_bf16 v[0:3], v[34:37], v[38:41], v[0:3]
	s_waitcnt vmcnt(8)
	v_mfma_f32_16x16x32_bf16 v[6:9], v[42:45], v[50:53], v[6:9]
	s_waitcnt vmcnt(6)
	v_mfma_f32_16x16x32_bf16 v[0:3], v[54:57], v[58:61], v[0:3]
	s_waitcnt vmcnt(4)
	v_mfma_f32_16x16x32_bf16 v[6:9], v[62:65], v[66:69], v[6:9]
	s_waitcnt vmcnt(2)
	v_mfma_f32_16x16x32_bf16 v[0:3], v[70:73], v[74:77], v[0:3]
	s_waitcnt vmcnt(0)
	v_mfma_f32_16x16x32_bf16 v[6:9], v[78:81], v[82:85], v[6:9]
	s_cbranch_scc1 .LBB0_802
	s_lshl_b32 s4, s13, 1
	s_lshl_b32 s5, s13, 7
	s_and_b32 s4, s4, -16
	s_and_b32 s5, s5, 0x380
	v_add_u32_e32 v12, s5, v14
	v_add_u32_e32 v10, s4, v16
	v_ashrrev_i32_e32 v11, 31, v10
	v_or_b32_e32 v12, v12, v15
	v_pk_add_f32 v[6:7], v[0:1], v[6:7]
	v_lshlrev_b64 v[0:1], 12, v[10:11]
	v_ashrrev_i32_e32 v13, 31, v12
	v_pk_add_f32 v[8:9], v[2:3], v[8:9]
	v_lshl_add_u64 v[2:3], s[16:17], 0, v[0:1]
	v_lshlrev_b64 v[18:19], 2, v[12:13]
	v_lshl_add_u64 v[0:1], s[6:7], 0, v[0:1]
	v_lshl_add_u64 v[0:1], v[0:1], 0, v[18:19]
	v_lshl_add_u64 v[20:21], v[2:3], 0, v[18:19]
	global_load_dwordx4 v[0:3], v[0:1], off
	s_waitcnt vmcnt(0)
	v_pk_add_f32 v[2:3], v[8:9], v[2:3]
	v_pk_add_f32 v[0:1], v[6:7], v[0:1]
	global_store_dwordx4 v[20:21], v[0:3], off
	v_cvt_pk_bf16_f32 v6, v0, v1
	v_cvt_pk_bf16_f32 v7, v2, v3
	v_lshlrev_b64 v[8:9], 11, v[10:11]
	v_lshl_add_u64 v[8:9], s[18:19], 0, v[8:9]
	v_mul_f32_e32 v1, v1, v1
	v_fmac_f32_e32 v1, v0, v0
	v_mul_f32_e32 v0, v3, v3
	v_fmac_f32_e32 v0, v2, v2
	v_and_b32_e32 v2, 64, v240
	v_add_f32_e32 v0, v1, v0
	v_xor_b32_e32 v1, 16, v240
	v_add_u32_e32 v2, 64, v2
	v_cmp_lt_i32_e64 s[4:5], v1, v2
	v_lshl_add_u64 v[8:9], v[12:13], 1, v[8:9]
	global_store_dwordx2 v[8:9], v[6:7], off
	v_cndmask_b32_e64 v1, v240, v1, s[4:5]
	v_lshlrev_b32_e32 v1, 2, v1
	ds_bpermute_b32 v1, v1, v0
	s_waitcnt lgkmcnt(0)
	v_add_f32_e32 v0, v0, v1
	v_xor_b32_e32 v1, 32, v240
	v_cmp_lt_i32_e64 s[4:5], v1, v2
	s_nop 1
	v_cndmask_b32_e64 v1, v240, v1, s[4:5]
	v_lshlrev_b32_e32 v1, 2, v1
	ds_bpermute_b32 v1, v1, v0
	s_and_saveexec_b64 s[4:5], vcc
	s_cbranch_execz .LBB0_800
	s_waitcnt lgkmcnt(0)
	v_add_f32_e32 v2, v0, v1
	v_lshl_add_u64 v[0:1], v[10:11], 2, s[22:23]
	global_atomic_add_f32 v[0:1], v2, off
	s_branch .LBB0_800
